# scan->gate XCD-local seam also waits (already satisfied) for every gdn_pre of the launch, since the gated rows are written over other batches' q|k|v input
# baseline (speedup 1.0000x reference)
.LBB0_308:
	s_waitcnt vmcnt(0)
	v_readfirstlane_b32 s4, v194
	s_cmp_gt_u32 s4, 63
	v_readlane_b32 s77, v242, 9
	v_readlane_b32 s78, v241, 13
	v_readlane_b32 s40, v241, 12
	v_readlane_b32 s41, v241, 4
	s_barrier
	s_cbranch_scc1 .LBB0_362
	v_mbcnt_lo_u32_b32 v0, -1, 0
	v_mbcnt_hi_u32_b32 v0, -1, v0
	s_nop 0
	v_cmp_eq_u32_e32 vcc, 0, v0
	s_and_saveexec_b64 s[6:7], vcc
	s_cbranch_execz .LBB0_361
	v_mov_b32_e32 v0, 0x23ff0
	s_waitcnt vmcnt(0) lgkmcnt(0)
	ds_read_b128 v[0:3], v0
	s_waitcnt lgkmcnt(0)
	s_add_u32 s4, s92, 0x510000
	s_addc_u32 s5, s93, 0
	v_mov_b32_e32 v6, 0x3e0c
	v_mov_b32_e32 v7, 1
	global_atomic_add v6, v7, s[4:5]
	v_readfirstlane_b32 s8, v2
	s_nop 0
	s_cmp_eq_u32 s8, 0
	s_cbranch_scc1 .Lfb_slow_1
	v_readfirstlane_b32 s9, v0
	s_cmp_eq_u32 s9, 32
	s_cbranch_scc0 .Lfb_xcd_1
	buffer_inv sc1
	s_getreg_b32 s8, hwreg(HW_REG_XCC_ID, 0, 4)
	s_and_b32 s8, s8, 7
	s_lshl_b32 s8, s8, 8
	s_add_u32 s8, s8, 0x3600
	s_add_u32 s4, s92, 0x510000
	s_addc_u32 s5, s93, 0
	v_mov_b32_e32 v7, 1
	s_bfe_u32 s9, s2, 0x20006
	s_lshl_b32 s9, s9, 2
	s_add_u32 s9, s9, s8
	s_add_u32 s9, s9, 0xe0
	v_mov_b32_e32 v6, s9
	global_atomic_add v6, v7, s[4:5]
	s_bfe_u32 s9, s2, 0x20006
	s_lshl_b32 s9, s9, 2
	s_add_u32 s9, s9, s8
	s_add_u32 s9, s9, 0xe0
	v_mov_b32_e32 v6, s9
	s_mov_b32 s9, 0

.Lscan_loop:
	s_and_b32 s7, s6, 3
	s_lshl_b32 s7, s7, 12
	v_add_u32_e32 v23, s7, v22
	ds_read_b128 v[32:35], v10 offset:0
	ds_read_b128 v[48:51], v11 offset:0
	ds_read_b128 v[36:39], v10 offset:64
	ds_read_b128 v[52:55], v12 offset:0
	ds_read_b128 v[40:43], v10 offset:128
	ds_read_b128 v[56:59], v13 offset:0
	ds_read_b128 v[44:47], v10 offset:192
	ds_read_b128 v[60:63], v14 offset:0
	ds_read_u16 v80, v23 offset:0
	ds_read_u16 v81, v23 offset:64
	ds_read_u16 v82, v23 offset:128
	ds_read_u16 v83, v23 offset:192
	s_add_u32 s33, s6, 1
	s_min_u32 s33, s33, 31
	s_add_u32 s36, s6, 2
	s_min_u32 s36, s36, 31
	v_readlane_b32 s37, v24, s6
	s_nop 1
	v_mul_f32_e32 v92, s37, v92
	v_mul_f32_e32 v93, s37, v93
	v_mul_f32_e32 v94, s37, v94
	v_mul_f32_e32 v95, s37, v95
	v_mul_f32_e32 v96, s37, v96
	v_mul_f32_e32 v97, s37, v97
	v_mul_f32_e32 v98, s37, v98
	v_mul_f32_e32 v99, s37, v99
	s_waitcnt lgkmcnt(10)
	v_mfma_f32_16x16x32_bf16 v[84:87], v[48:51], v[32:35], 0
	s_waitcnt lgkmcnt(8)
	v_mfma_f32_16x16x32_bf16 v[84:87], v[52:55], v[36:39], v[84:87]
	s_waitcnt lgkmcnt(6)
	v_mfma_f32_16x16x32_bf16 v[84:87], v[56:59], v[40:43], v[84:87]
	s_waitcnt lgkmcnt(4)
	v_mfma_f32_16x16x32_bf16 v[84:87], v[60:63], v[44:47], v[84:87]
	ds_read_b128 v[64:67], v11 offset:32768
	ds_read_b128 v[68:71], v12 offset:32768
	ds_read_b128 v[72:75], v13 offset:32768
	ds_read_b128 v[76:79], v14 offset:32768
	s_waitcnt lgkmcnt(4)
	v_lshlrev_b32_e32 v80, 16, v80
	v_lshlrev_b32_e32 v81, 16, v81
	v_lshlrev_b32_e32 v82, 16, v82
	v_lshlrev_b32_e32 v83, 16, v83
	v_sub_f32_e32 v26, v80, v84
	v_sub_f32_e32 v27, v81, v85
	v_sub_f32_e32 v28, v82, v86
	v_sub_f32_e32 v29, v83, v87
	v_cvt_pk_bf16_f32 v26, v26, v27
	v_cvt_pk_bf16_f32 v27, v28, v29
	ds_write_b64 v20, v[26:27]
	s_lshl_b32 s7, s33, 14
	s_add_u32 s26, s14, s7
	s_addc_u32 s27, s15, 0
	s_add_i32 m0, s30, 0x14000
	s_nop 0
	global_load_lds_dwordx4 v5, s[26:27]
	s_add_i32 m0, s30, 0x14400
	s_nop 0
	global_load_lds_dwordx4 v6, s[26:27]
	s_lshl_b32 s7, s33, 13
	s_add_u32 s28, s18, s7
	s_addc_u32 s29, s19, 0
	s_add_i32 m0, s31, 0x1a000
	s_nop 0
	global_load_lds_dwordx4 v7, s[28:29]
	s_lshl_b32 s7, s36, 14
	s_add_u32 s26, s24, s7
	s_addc_u32 s27, s25, 0
	s_add_u32 s8, s6, 2
	s_and_b32 s8, s8, 3
	s_lshl_b32 s8, s8, 12
	s_add_u32 s8, s8, s32
	s_add_i32 m0, s8, 0x1f400
	s_nop 0
	global_load_lds_dwordx4 v8, s[26:27]
	s_waitcnt vmcnt(10) lgkmcnt(0)
	s_barrier
	ds_read_b128 v[100:103], v19
	ds_read_b128 v[108:111], v15 offset:0
	ds_read_b128 v[112:115], v15 offset:2048
	ds_read_b128 v[104:107], v19 offset:64
	ds_read_b128 v[116:119], v16 offset:0
	ds_read_b128 v[120:123], v16 offset:2048
	ds_read_b128 v[124:127], v17 offset:0
	ds_read_b128 v[128:131], v18 offset:0
	v_mfma_f32_16x16x32_bf16 v[88:91], v[32:35], v[64:67], 0
	v_mfma_f32_16x16x32_bf16 v[88:91], v[36:39], v[68:71], v[88:91]
	v_mfma_f32_16x16x32_bf16 v[88:91], v[40:43], v[72:75], v[88:91]
	v_mfma_f32_16x16x32_bf16 v[88:91], v[44:47], v[76:79], v[88:91]
	s_waitcnt lgkmcnt(6)
	v_mfma_f32_16x16x32_bf16 v[92:95], v[108:111], v[100:103], v[92:95]
	s_waitcnt lgkmcnt(5)
	v_mfma_f32_16x16x32_bf16 v[96:99], v[112:115], v[100:103], v[96:99]
	s_waitcnt lgkmcnt(3)
	v_mfma_f32_16x16x32_bf16 v[92:95], v[116:119], v[104:107], v[92:95]
	s_waitcnt lgkmcnt(2)
	v_mfma_f32_16x16x32_bf16 v[96:99], v[120:123], v[104:107], v[96:99]
	s_waitcnt lgkmcnt(1)
	v_mfma_f32_16x16x32_bf16 v[88:91], v[100:103], v[124:127], v[88:91]
	s_waitcnt lgkmcnt(0)
	v_mfma_f32_16x16x32_bf16 v[88:91], v[104:107], v[128:131], v[88:91]
	s_lshl_b32 s7, s6, 14
	s_add_u32 s28, s24, s7
	s_addc_u32 s29, s25, 0
	s_nop 1
	v_cvt_pk_bf16_f32 v26, v92, v93
	v_cvt_pk_bf16_f32 v27, v94, v95
	v_cvt_pk_bf16_f32 v28, v96, v97
	v_cvt_pk_bf16_f32 v29, v98, v99
	ds_write_b64 v21, v[26:27]
	ds_write_b64 v21, v[28:29] offset:32
	s_lshl_b32 s7, s36, 14
	s_add_u32 s26, s10, s7
	s_addc_u32 s27, s11, 0
	s_add_i32 m0, s30, 0x0
	s_nop 0
	global_load_lds_dwordx4 v3, s[26:27]
	s_add_i32 m0, s30, 0x400
	s_nop 0
	global_load_lds_dwordx4 v4, s[26:27]
	s_lshl_b32 s7, s36, 14
	s_add_u32 s26, s12, s7
	s_addc_u32 s27, s13, 0
	s_add_i32 m0, s30, 0x8000
	s_nop 0
	global_load_lds_dwordx4 v3, s[26:27]
	s_add_i32 m0, s30, 0x8400
	s_nop 0
	global_load_lds_dwordx4 v4, s[26:27]
	v_cvt_pk_bf16_f32 v80, v88, v89
	v_cvt_pk_bf16_f32 v81, v90, v91
	global_store_dwordx2 v9, v[80:81], s[28:29]
	s_add_u32 s6, s6, 1
	s_waitcnt vmcnt(10) lgkmcnt(0)
	s_barrier
	s_and_b32 s7, s6, 3
	s_lshl_b32 s7, s7, 12
	v_add_u32_e32 v23, s7, v22
	ds_read_b128 v[32:35], v10 offset:0
	ds_read_b128 v[48:51], v11 offset:16384
	ds_read_b128 v[36:39], v10 offset:64
	ds_read_b128 v[52:55], v12 offset:16384
	ds_read_b128 v[40:43], v10 offset:128
	ds_read_b128 v[56:59], v13 offset:16384
	ds_read_b128 v[44:47], v10 offset:192
	ds_read_b128 v[60:63], v14 offset:16384
	ds_read_u16 v80, v23 offset:0
	ds_read_u16 v81, v23 offset:64
	ds_read_u16 v82, v23 offset:128
	ds_read_u16 v83, v23 offset:192
	s_add_u32 s33, s6, 1
	s_min_u32 s33, s33, 31
	s_add_u32 s36, s6, 2
	s_min_u32 s36, s36, 31
	v_readlane_b32 s37, v24, s6
	s_nop 1
	v_mul_f32_e32 v92, s37, v92
	v_mul_f32_e32 v93, s37, v93
	v_mul_f32_e32 v94, s37, v94
	v_mul_f32_e32 v95, s37, v95
	v_mul_f32_e32 v96, s37, v96
	v_mul_f32_e32 v97, s37, v97
	v_mul_f32_e32 v98, s37, v98
	v_mul_f32_e32 v99, s37, v99
	s_waitcnt lgkmcnt(10)
	v_mfma_f32_16x16x32_bf16 v[84:87], v[48:51], v[32:35], 0
	s_waitcnt lgkmcnt(8)
	v_mfma_f32_16x16x32_bf16 v[84:87], v[52:55], v[36:39], v[84:87]
	s_waitcnt lgkmcnt(6)
	v_mfma_f32_16x16x32_bf16 v[84:87], v[56:59], v[40:43], v[84:87]
	s_waitcnt lgkmcnt(4)
	v_mfma_f32_16x16x32_bf16 v[84:87], v[60:63], v[44:47], v[84:87]
	ds_read_b128 v[64:67], v11 offset:49152
	ds_read_b128 v[68:71], v12 offset:49152
	ds_read_b128 v[72:75], v13 offset:49152
	ds_read_b128 v[76:79], v14 offset:49152
	s_waitcnt lgkmcnt(4)
	v_lshlrev_b32_e32 v80, 16, v80
	v_lshlrev_b32_e32 v81, 16, v81
	v_lshlrev_b32_e32 v82, 16, v82
	v_lshlrev_b32_e32 v83, 16, v83
	v_sub_f32_e32 v26, v80, v84
	v_sub_f32_e32 v27, v81, v85
	v_sub_f32_e32 v28, v82, v86
	v_sub_f32_e32 v29, v83, v87
	v_cvt_pk_bf16_f32 v26, v26, v27
	v_cvt_pk_bf16_f32 v27, v28, v29
	ds_write_b64 v20, v[26:27]
	s_lshl_b32 s7, s33, 14
	s_add_u32 s26, s14, s7
	s_addc_u32 s27, s15, 0
	s_add_i32 m0, s30, 0x10000
	s_nop 0
	global_load_lds_dwordx4 v5, s[26:27]
	s_add_i32 m0, s30, 0x10400
	s_nop 0
	global_load_lds_dwordx4 v6, s[26:27]
	s_lshl_b32 s7, s33, 13
	s_add_u32 s28, s18, s7
	s_addc_u32 s29, s19, 0
	s_add_i32 m0, s31, 0x18000
	s_nop 0
	global_load_lds_dwordx4 v7, s[28:29]
	s_lshl_b32 s7, s36, 14
	s_add_u32 s26, s24, s7
	s_addc_u32 s27, s25, 0
	s_add_u32 s8, s6, 2
	s_and_b32 s8, s8, 3
	s_lshl_b32 s8, s8, 12
	s_add_u32 s8, s8, s32
	s_add_i32 m0, s8, 0x1f400
	s_nop 0
	global_load_lds_dwordx4 v8, s[26:27]
	s_waitcnt vmcnt(10) lgkmcnt(0)
	s_barrier
	ds_read_b128 v[100:103], v19
	ds_read_b128 v[108:111], v15 offset:16384
	ds_read_b128 v[112:115], v15 offset:18432
	ds_read_b128 v[104:107], v19 offset:64
	ds_read_b128 v[116:119], v16 offset:16384
	ds_read_b128 v[120:123], v16 offset:18432
	ds_read_b128 v[124:127], v17 offset:8192
	ds_read_b128 v[128:131], v18 offset:8192
	v_mfma_f32_16x16x32_bf16 v[88:91], v[32:35], v[64:67], 0
	v_mfma_f32_16x16x32_bf16 v[88:91], v[36:39], v[68:71], v[88:91]
	v_mfma_f32_16x16x32_bf16 v[88:91], v[40:43], v[72:75], v[88:91]
	v_mfma_f32_16x16x32_bf16 v[88:91], v[44:47], v[76:79], v[88:91]
	s_waitcnt lgkmcnt(6)
	v_mfma_f32_16x16x32_bf16 v[92:95], v[108:111], v[100:103], v[92:95]
	s_waitcnt lgkmcnt(5)
	v_mfma_f32_16x16x32_bf16 v[96:99], v[112:115], v[100:103], v[96:99]
	s_waitcnt lgkmcnt(3)
	v_mfma_f32_16x16x32_bf16 v[92:95], v[116:119], v[104:107], v[92:95]
	s_waitcnt lgkmcnt(2)
	v_mfma_f32_16x16x32_bf16 v[96:99], v[120:123], v[104:107], v[96:99]
	s_waitcnt lgkmcnt(1)
	v_mfma_f32_16x16x32_bf16 v[88:91], v[100:103], v[124:127], v[88:91]
	s_waitcnt lgkmcnt(0)
	v_mfma_f32_16x16x32_bf16 v[88:91], v[104:107], v[128:131], v[88:91]
	s_lshl_b32 s7, s6, 14
	s_add_u32 s28, s24, s7
	s_addc_u32 s29, s25, 0
	s_nop 1
	v_cvt_pk_bf16_f32 v26, v92, v93
	v_cvt_pk_bf16_f32 v27, v94, v95
	v_cvt_pk_bf16_f32 v28, v96, v97
	v_cvt_pk_bf16_f32 v29, v98, v99
	ds_write_b64 v21, v[26:27]
	ds_write_b64 v21, v[28:29] offset:32
	s_lshl_b32 s7, s36, 14
	s_add_u32 s26, s10, s7
	s_addc_u32 s27, s11, 0
	s_add_i32 m0, s30, 0x4000
	s_nop 0
	global_load_lds_dwordx4 v3, s[26:27]
	s_add_i32 m0, s30, 0x4400
	s_nop 0
	global_load_lds_dwordx4 v4, s[26:27]
	s_lshl_b32 s7, s36, 14
	s_add_u32 s26, s12, s7
	s_addc_u32 s27, s13, 0
	s_add_i32 m0, s30, 0xc000
	s_nop 0
	global_load_lds_dwordx4 v3, s[26:27]
	s_add_i32 m0, s30, 0xc400
	s_nop 0
	global_load_lds_dwordx4 v4, s[26:27]
	v_cvt_pk_bf16_f32 v80, v88, v89
	v_cvt_pk_bf16_f32 v81, v90, v91
	global_store_dwordx2 v9, v[80:81], s[28:29]
	s_add_u32 s6, s6, 1
	s_waitcnt vmcnt(10) lgkmcnt(0)
	s_barrier
	s_cmp_lt_u32 s6, 32
	s_cbranch_scc1 .Lscan_loop
	s_lshl_b32 s56, s77, 5
	s_and_b32 s57, s40, 3
	s_lshl_b32 s72, s40, 5
	s_waitcnt vmcnt(0)
	v_readfirstlane_b32 s3, v194
	s_cmp_gt_u32 s3, 63
	s_barrier
	s_cbranch_scc1 .LBB0_421
	s_waitcnt vmcnt(2)
	v_mbcnt_lo_u32_b32 v0, -1, 0
	v_mbcnt_hi_u32_b32 v0, -1, v0
	s_nop 0
	v_cmp_eq_u32_e32 vcc, 0, v0
	s_and_saveexec_b64 s[6:7], vcc
	s_cbranch_execz .LBB0_420
	v_mov_b32_e32 v0, 0x23ff0
	s_waitcnt vmcnt(0) lgkmcnt(0)
	ds_read_b128 v[0:3], v0
	s_waitcnt lgkmcnt(0)
	s_add_u32 s4, s92, 0x510000
	s_addc_u32 s5, s93, 0
	v_mov_b32_e32 v6, 0x3e00
	v_mov_b32_e32 v7, 1
	global_atomic_add v6, v7, s[4:5]
	v_readfirstlane_b32 s3, v2
	s_nop 0
	s_cmp_eq_u32 s3, 0
	s_cbranch_scc1 .Lfb_slow_2
	v_readfirstlane_b32 s8, v0
	s_cmp_eq_u32 s8, 32
	s_cbranch_scc0 .Lfb_xcd_2
	buffer_inv sc1
	s_getreg_b32 s3, hwreg(HW_REG_XCC_ID, 0, 4)
	s_and_b32 s3, s3, 7
	s_lshl_b32 s3, s3, 8
	s_add_u32 s3, s3, 0x3600
	s_add_u32 s4, s92, 0x510000
	s_addc_u32 s5, s93, 0
	v_mov_b32_e32 v7, 1
	s_mov_b32 s8, s3
	s_add_u32 s8, s8, 0x5c
	v_mov_b32_e32 v6, s8
	global_atomic_add v6, v7, s[4:5]
	s_mov_b32 s8, s3
	s_add_u32 s8, s8, 0x5c
	v_mov_b32_e32 v6, s8
	s_mov_b32 s8, 0x3e0c
	v_mov_b32_e32 v4, s8
	s_mov_b32 s8, 0
.Lfb_gs_2:
	global_load_dword v8, v6, s[4:5] sc1
	global_load_dword v5, v4, s[4:5] sc1
	s_waitcnt vmcnt(0)
	v_add_u32_e32 v8, -32, v8
	v_add_u32_e32 v5, -256, v5
	v_min_i32_e32 v8, v8, v5
	v_cmp_le_i32_e32 vcc, 0, v8
	s_cbranch_vccnz .Lfb_done_2
	s_sleep 1
	s_add_u32 s8, s8, 1
	s_cmp_lt_u32 s8, 0x40000
	s_cbranch_scc1 .Lfb_gs_2
	s_branch .Lfb_done_2
.Lfb_xcd_2:
	s_add_u32 s4, s92, 0x510000
	s_addc_u32 s5, s93, 0
	v_mov_b32_e32 v6, 0x3e0c
	s_mov_b32 s8, 0
.Lfb_gp_2:
	global_load_dword v8, v6, s[4:5] sc1
	s_waitcnt vmcnt(0)
	v_cmp_le_u32_e32 vcc, 0x100, v8
	s_cbranch_vccnz .Lfb_gpd_2
	s_sleep 1
	s_add_u32 s8, s8, 1
	s_cmp_lt_u32 s8, 0x40000
	s_cbranch_scc1 .Lfb_gp_2
